# v_f1 + waves 4-7 priority raised around PV0 and PV2 MFMA blocks only (alternating MFMA-collision winner)
# speedup vs baseline: 1.0007x; 1.0006x over previous
.Latt_dma0:
	ds_read_b64_tr_b16 v[152:153], v156 offset:17408
	ds_read_b64_tr_b16 v[154:155], v156 offset:17920
	ds_read_b64_tr_b16 v[148:149], v156 offset:21504
	ds_read_b64_tr_b16 v[150:151], v156 offset:22016
	ds_read_b64_tr_b16 v[100:101], v156 offset:25600
	ds_read_b64_tr_b16 v[102:103], v156 offset:26112
	ds_read_b64_tr_b16 v[96:97], v156 offset:29696
	ds_read_b64_tr_b16 v[98:99], v156 offset:30208
	s_cmp_lg_u32 s89, 0
	s_cbranch_scc0 .Lpvq1
	s_setprio 1
.Lpvq1:
	s_waitcnt lgkmcnt(14)
	v_mfma_f32_32x32x16_bf16 v[48:63], v[216:219], v[144:147], v[48:63]
	s_andn2_b64 vcc, exec, s[50:51]
	s_waitcnt lgkmcnt(12)
	v_mfma_f32_32x32x16_bf16 v[32:47], v[216:219], v[140:143], v[32:47]
	s_waitcnt lgkmcnt(10)
	v_mfma_f32_32x32x16_bf16 v[16:31], v[216:219], v[136:139], v[16:31]
	s_waitcnt lgkmcnt(8)
	v_mfma_f32_32x32x16_bf16 v[0:15], v[216:219], v[132:135], v[0:15]
	v_cndmask_b32_e64 v132, 0, 1, s[50:51]
	v_cmp_ne_u32_e64 s[6:7], 1, v132
	v_mfma_f32_32x32x16_bf16 v[64:79], v[216:219], v[128:131], v[64:79]
	s_setprio 0

.Latt_dma2:
	ds_read_b64_tr_b16 v[100:101], v156 offset:19456
	ds_read_b64_tr_b16 v[102:103], v156 offset:19968
	ds_read_b64_tr_b16 v[96:97], v156 offset:23552
	ds_read_b64_tr_b16 v[98:99], v156 offset:24064
	ds_read_b64_tr_b16 v[84:85], v156 offset:27648
	ds_read_b64_tr_b16 v[86:87], v156 offset:28160
	ds_read_b64_tr_b16 v[80:81], v156 offset:31744
	ds_read_b64_tr_b16 v[82:83], v156 offset:32256
	s_cmp_lg_u32 s89, 0
	s_cbranch_scc0 .Lpvq3
	s_setprio 1
.Lpvq3:
	s_waitcnt lgkmcnt(14)
	v_mfma_f32_32x32x16_bf16 v[48:63], v[140:143], v[136:139], v[48:63]
	s_and_b64 vcc, exec, s[6:7]
	s_waitcnt lgkmcnt(12)
	v_mfma_f32_32x32x16_bf16 v[32:47], v[140:143], v[132:135], v[32:47]
	s_waitcnt lgkmcnt(10)
	v_mfma_f32_32x32x16_bf16 v[16:31], v[140:143], v[108:111], v[16:31]
	s_waitcnt lgkmcnt(8)
	v_mfma_f32_32x32x16_bf16 v[0:15], v[140:143], v[104:107], v[0:15]
	v_mfma_f32_32x32x16_bf16 v[64:79], v[140:143], v[128:131], v[64:79]
	s_setprio 0
	s_cbranch_vccnz .LBB0_1004
	s_add_u32 s6, s42, 0x480
	s_addc_u32 s7, s43, 0
	s_add_i32 s50, s86, s68
	s_addk_i32 s50, 0x2000
	s_mov_b32 s51, m0
	s_mov_b32 m0, s50
	s_nop 0
	global_load_lds_dwordx4 v212, s[6:7]
	s_mov_b32 m0, s51
	s_branch .LBB0_1004
